# stick-breaking loop header: the 8 done flags read by two ds_read_b128 (one LDS round trip) instead of 8 serialized ds_read_b32
# baseline (speedup 1.0000x reference)
.LBB0_460:
	s_and_b32 s69, s89, 1
	s_mul_i32 s16, s69, 0x4400
	s_add_i32 s18, s16, 0
	s_mul_i32 s16, s69, 0xc00
	s_add_i32 s22, s18, s16
	v_add_u32_e32 v64, s18, v158
	v_add_u32_e32 v65, v64, v159
	v_add_u32_e32 v64, v64, v201
	s_cmp_eq_u32 s89, 0
	s_waitcnt vmcnt(0)
	ds_write_b128 v65, v[126:129]
	ds_write_b128 v64, v[122:125]
	v_add_u32_e32 v64, s22, v158
	s_cselect_b64 s[16:17], -1, 0
	v_add_u32_e32 v65, v64, v202
	v_add_u32_e32 v64, v64, v203
	s_and_b64 vcc, exec, s[16:17]
	ds_write_b128 v65, v[118:121] offset:34816
	ds_write_b128 v64, v[114:117] offset:34816
	s_waitcnt lgkmcnt(0)
	s_barrier
	s_cbranch_vccnz .LBB0_462
	s_and_b32 s16, s87, 8
	s_xor_b32 s17, s16, 8
	s_lshl_b32 s17, s17, 2
	s_add_i32 s17, s17, 0x12c00
	v_mov_b32_e32 v72, s17
	ds_read_b128 v[64:67], v72
	ds_read_b128 v[68:71], v72 offset:16
	s_waitcnt lgkmcnt(0)
	v_and_b32_e32 v64, v64, v65
	v_and_b32_e32 v66, v66, v67
	v_and_b32_e32 v68, v68, v69
	v_and_b32_e32 v70, v70, v71
	v_and_b32_e32 v64, v64, v66
	v_and_b32_e32 v68, v68, v70
	v_and_b32_e32 v64, v64, v68
	v_and_b32_e32 v64, 1, v64
	v_cmp_eq_u32_e64 s[16:17], 0, v64
